# conversions split over four idle windows (P1, P3 tail, P6 tail, P7b one-task workgroups); no tile permutation
# speedup vs baseline: 1.0024x; 1.0024x over previous
; template <int PART>
; __device__ __forceinline__ void prologue(const Params& P, LAS unsigned char* lds, int gw, int NGW, int wave, int lane) {
;     ...
;     for (int it = gw; it < NITEMS; it += NGW) {
;         int r = it;
;         if (PART == 0) { if (r >= I_ADA) break; r += I_FIRST; } else { if (r >= NITEMS - I_ADA) break; if (r >= I_FIRST) r += I_ADA; }
.Lcv_tailmap:
	s_cmp_eq_u32 s99, 1
	s_cbranch_scc0 .Lcv_tailmap3
	s_cmpk_gt_i32 s26, 0x5ff
	s_cbranch_scc1 .LBB0_319
	s_add_i32 s22, s26, 0x3110
	s_branch .Lcv_go
.Lcv_tailmap3:
	s_cmp_eq_u32 s99, 2
	s_cbranch_scc0 .Lcv_tailmap7
	s_cmpk_gt_i32 s26, 0x108f
	s_cbranch_scc1 .LBB0_319
	s_add_i32 s22, s26, 0x2100
	s_cmpk_lt_i32 s26, 0x1010
	s_cbranch_scc1 .Lcv_go
	s_add_i32 s22, s26, 0x3900
	s_branch .Lcv_go
.Lcv_tailmap7:
	s_cmpk_gt_i32 s26, 0x107f
	s_cbranch_scc1 .LBB0_319
	s_add_i32 s22, s26, 0xb00
	s_cmpk_lt_i32 s26, 0xb00
	s_cbranch_scc1 .Lcv_go
	s_add_i32 s22, s26, 0x1080

; __device__ __forceinline__ unsigned xb_add(unsigned* p, unsigned v) { return __hip_atomic_fetch_add(p, v, __ATOMIC_RELAXED, __HIP_MEMORY_SCOPE_AGENT); }
; __device__ __forceinline__ void xcd_barrier(const XcdBarrier& b, bool leader) {
;     asm volatile("s_waitcnt vmcnt(0)" ::: "memory");
;     __syncthreads();
;     if (leader) {
;         unsigned* bar = b.bar;
;         __builtin_amdgcn_s_waitcnt(0);
;         unsigned nloc = b.st[0], nx = b.st[1];
;         if (nloc == 0u) { xcd_barrier_complete(bar, b.x, nloc, nx); b.st[0] = nloc; b.st[1] = nx; }
;         const unsigned old = xb_add(&bar[XB_XSUB(b.x)], 1u);
;         const unsigned gen = old / nloc;
;         if (old + 1u == (gen + 1u) * nloc) {
.LBB0_345:
	s_cmp_eq_u32 s99, 1
	s_cbranch_scc1 .Lcv_ret
	s_cmp_eq_u32 s99, 2
	s_cbranch_scc1 .Lcv_ret3
	s_cmp_eq_u32 s99, 3
	s_cbranch_scc1 .Lcv_tr1_ret
	s_waitcnt vmcnt(0)
	s_waitcnt vmcnt(0) lgkmcnt(0)
	s_barrier
	s_and_saveexec_b64 s[4:5], s[88:89]
	s_cbranch_execz .LBB0_397
	s_add_i32 s6, 0, 0x23fc0
	v_mov_b32_e32 v0, s6
	s_waitcnt vmcnt(0) expcnt(0) lgkmcnt(0)
	ds_read_b32 v2, v0
	s_add_i32 s6, 0, 0x23fc4
	v_mov_b32_e32 v0, s6
	ds_read_b32 v0, v0
	s_waitcnt lgkmcnt(1)
	v_cmp_ne_u32_e32 vcc, 0, v2
	s_cbranch_vccnz .LBB0_361
	s_add_u32 s6, s76, 0x1000
	s_addc_u32 s7, s77, 0
	s_add_u32 s8, s76, 0x1100
	s_addc_u32 s9, s77, 0
	s_add_u32 s10, s76, 0x1200
	s_addc_u32 s11, s77, 0
	s_mul_i32 s20, s79, s74
	s_add_u32 s12, s76, 0x1300
	s_mul_i32 s20, s20, s78
	s_addc_u32 s13, s77, 0
	s_mov_b32 s21, 1
	v_mov_b32_e32 v16, 0
	s_branch .LBB0_349

; #define PG8_BAR __builtin_amdgcn_s_barrier()
; #define PG8_ZERO() do { _Pragma("unroll") for (int a = 0; a < 2; ++a) _Pragma("unroll") for (int b = 0; b < 2; ++b) _Pragma("unroll") for (int m = 0; m < 4; ++m) _Pragma("unroll") for (int n = 0; n < 2; ++n) acc[a][b][m][n] = (f32x4){0.f, 0.f, 0.f, 0.f}; } while (0)
; template <class Epi, class Sched>
; __device__ __forceinline__ void gemm_phase(LAS unsigned char* lds, const Gemm g, const Sched& S, const Epi& E, int wid) {
;     ...
;         if (!has_next) break;
;         if (!keep) PG8_ZERO();
;         cur = nxt; cA = nA; cB = nB; ++ui;
;         if (wr == 1) PG8_BAR;
.LBB0_966:
	s_or_b64 exec, exec, s[6:7]
	s_andn2_b64 vcc, exec, s[10:11]
	s_mov_b64 s[4:5], -1
	s_cbranch_vccnz .LBB0_735
	s_andn2_b64 vcc, exec, s[18:19]
	s_cbranch_vccnz .LBB0_734
	s_barrier
	s_branch .LBB0_734
.Lcv_tr1_fwd:
	s_branch .Lcv_pre
.Lcv_tr1_ret:
	s_branch .Lcv_tr2_ret
.LBB0_969:
	s_waitcnt vmcnt(0)
	s_barrier

.LBB0_1441:
	s_movk_i32 s12, 0x110
	v_mad_u64_u32 v[4:5], s[12:13], v152, s12, v[2:3]
	s_waitcnt vmcnt(0)
	ds_write_b128 v4, v[60:63]
	s_or_b64 exec, exec, s[8:9]
	s_and_saveexec_b64 s[8:9], s[16:17]
	s_cbranch_execnz .LBB0_1293
	s_branch .LBB0_1294
.Lcv_tr2_fwd:
	s_branch .Lcv_tr1_fwd
.Lcv_tr2_ret:
	s_branch .Lcv_ret7
.LBB0_1442:
	s_or_b64 exec, exec, s[14:15]
	s_xor_b64 s[12:13], s[16:17], -1
	s_and_saveexec_b64 s[14:15], s[12:13]
	s_xor_b64 s[14:15], exec, s[14:15]
	s_cbranch_execz .LBB0_1445
	s_mov_b64 s[12:13], exec
	v_mbcnt_lo_u32_b32 v0, s12, 0
	v_mbcnt_hi_u32_b32 v0, s13, v0
	v_cmp_eq_u32_e32 vcc, 0, v0
	s_and_b64 s[14:15], exec, vcc
	s_mov_b64 exec, s[14:15]
	s_cbranch_execz .LBB0_1445
	s_bcnt1_i32_b64 s3, s[12:13]
	v_mov_b32_e32 v0, 0
	v_mov_b32_e32 v1, s3
	global_atomic_add v0, v1, s[76:77] offset:512

; #define tid opq((wave << 6) | lane_now())
; __global__ void __launch_bounds__(NTHR, 2) fwd_megakernel(Params P) {
;     ...
;             if (G == 256) { const int slot = (wg - 64) >> 3;
;                 { const int task = (wg & 7) * 32 + slot; rglru_task(P, lds, task >> 5, (task >> 2) & 7, task & 3, tid, RG_SPLIT, 16); }
;                 if (slot < 8) { const int task = (wg & 7) * 32 + 24 + slot; rglru_task(P, lds, task >> 5, (task >> 2) & 7, task & 3, tid, RG_SPLIT, 16); } }
;             else for (int task = wg - 64; task < 256; task += G - 64) rglru_task(P, lds, task >> 5, (task >> 2) & 7, task & 3, tid, RG_SPLIT, 16);
;             if (wg < 96) rglru_task(P, lds, -1, (wg - 64) >> 2, (wg - 64) & 3, tid, 0, 1);
;             if (wg >= 128) for (int item = wg - 128; item < NS * NH; item += G - 128) delta_sample_item<0>(P, lds, item, tid);
.LBB0_1810:
.Lcv_disp7:
	s_cmpk_lt_u32 s2, 0x80
	s_cbranch_scc1 .LBB0_1821
	s_mov_b32 s99, 3
	v_readfirstlane_b32 s3, v167
	s_lshr_b32 s3, s3, 6
	s_sub_i32 s72, s2, 0x80
	s_lshl_b32 s72, s72, 3
	s_add_i32 s72, s72, s3
	s_addk_i32 s72, 0x120
	s_movk_i32 s12, 0x520
	s_branch .Lcv_tr2_fwd
.Lcv_ret7:
	s_mov_b32 s99, 0
	s_branch .LBB0_1821
	s_mov_b64 s[4:5], 0
